# c15 + LN-epilogue residual loads software-pipelined (3-4 rounds in flight) in phases 6,8,11,13
# speedup vs baseline: 1.0140x; 1.0140x over previous
.LBB0_975:
	v_mov_b32_e32 v130, v144
	s_lshl_b32 s3, s2, 5
	s_barrier
	s_lshl_b32 s4, s8, 8
	v_ashrrev_i32_e32 v128, 2, v130
	s_or_b32 s3, s4, s3
	v_and_b32_e32 v128, -4, v128
	v_add_u32_e32 v136, s3, v128
	s_lshl_b32 s3, s36, 8
	v_and_b32_e32 v138, 15, v130
	s_add_i32 s4, s3, s0
	v_or_b32_e32 v128, s4, v138
	v_ashrrev_i32_e32 v129, 31, v128
	v_ashrrev_i32_e32 v137, 31, v136
	v_lshlrev_b64 v[132:133], 12, v[128:129]
	v_lshl_add_u64 v[134:135], s[38:39], 0, v[132:133]
	v_lshlrev_b64 v[132:133], 2, v[136:137]
	v_lshl_add_u64 v[134:135], v[134:135], 0, v[132:133]
	v_mov_b32_e32 v238, v134
	v_mov_b32_e32 v239, v135
	s_mov_b32 s99, 0
	global_load_dwordx4 v[170:173], v[134:135], off
	global_load_dwordx4 v[174:177], v[134:135], off offset:64
	global_load_dwordx4 v[178:181], v[134:135], off offset:512
	global_load_dwordx4 v[182:185], v[134:135], off offset:576
	s_mov_b32 s98, 0x10000
	v_lshl_add_u64 v[226:227], v[238:239], 0, s[98:99]
	global_load_dwordx4 v[186:189], v[226:227], off
	global_load_dwordx4 v[190:193], v[226:227], off offset:64
	global_load_dwordx4 v[194:197], v[226:227], off offset:512
	global_load_dwordx4 v[198:201], v[226:227], off offset:576
	s_mov_b32 s98, 0x20000
	v_lshl_add_u64 v[226:227], v[238:239], 0, s[98:99]
	global_load_dwordx4 v[202:205], v[226:227], off
	global_load_dwordx4 v[206:209], v[226:227], off offset:64
	global_load_dwordx4 v[210:213], v[226:227], off offset:512
	global_load_dwordx4 v[214:217], v[226:227], off offset:576
	s_mov_b32 s98, 0x30000
	v_lshl_add_u64 v[226:227], v[238:239], 0, s[98:99]
	global_load_dwordx4 v[218:221], v[226:227], off
	global_load_dwordx4 v[222:225], v[226:227], off offset:64
	global_load_dwordx4 v[230:233], v[226:227], off offset:512
	global_load_dwordx4 v[234:237], v[226:227], off offset:576
	v_or_b32_e32 v134, 16, v128
	v_ashrrev_i32_e32 v135, 31, v134
	v_lshlrev_b64 v[134:135], 12, v[134:135]
	s_mov_b32 s4, 0x3fb504f3
	v_lshl_add_u64 v[134:135], s[38:39], 0, v[134:135]
	v_lshl_add_u64 v[134:135], v[134:135], 0, v[132:133]
	v_and_b32_e32 v131, 64, v144
	v_xor_b32_e32 v129, 16, v144
	v_add_u32_e32 v131, 64, v131
	v_cmp_lt_i32_e32 vcc, v129, v131
	s_lshl_b32 s2, s2, 3
	s_add_i32 s2, s2, 0
	v_cndmask_b32_e32 v129, v144, v129, vcc
	v_lshlrev_b32_e32 v129, 2, v129
	s_waitcnt vmcnt(12)
	v_pk_fma_f32 v[118:119], v[172:173], s[4:5], v[118:119] op_sel_hi:[1,0,1]
	v_pk_fma_f32 v[116:117], v[170:171], s[4:5], v[116:117] op_sel_hi:[1,0,1]
	v_pk_fma_f32 v[82:83], v[176:177], s[4:5], v[82:83] op_sel_hi:[1,0,1]
	v_pk_fma_f32 v[80:81], v[174:175], s[4:5], v[80:81] op_sel_hi:[1,0,1]
	v_pk_fma_f32 v[30:31], v[180:181], s[4:5], v[30:31] op_sel_hi:[1,0,1]
	v_pk_fma_f32 v[28:29], v[178:179], s[4:5], v[28:29] op_sel_hi:[1,0,1]
	v_pk_fma_f32 v[2:3], v[184:185], s[4:5], v[2:3] op_sel_hi:[1,0,1]
	v_pk_fma_f32 v[0:1], v[182:183], s[4:5], v[0:1] op_sel_hi:[1,0,1]
	s_nop 0
	s_mov_b32 s98, 0x80000
	v_lshl_add_u64 v[226:227], v[238:239], 0, s[98:99]
	global_load_dwordx4 v[170:173], v[226:227], off
	global_load_dwordx4 v[174:177], v[226:227], off offset:64
	global_load_dwordx4 v[178:181], v[226:227], off offset:512
	global_load_dwordx4 v[182:185], v[226:227], off offset:576
	v_or_b32_e32 v134, 32, v128
	v_ashrrev_i32_e32 v135, 31, v134
	v_lshlrev_b64 v[134:135], 12, v[134:135]
	v_lshl_add_u64 v[134:135], s[38:39], 0, v[134:135]
	v_lshl_add_u64 v[134:135], v[134:135], 0, v[132:133]
	v_mov_b32_e32 v158, v117
	v_mov_b32_e32 v159, v118
	v_mov_b32_e32 v160, v116
	v_mov_b32_e32 v161, v119
	v_mov_b32_e32 v162, v81
	v_mov_b32_e32 v163, v82
	v_mov_b32_e32 v164, v80
	v_mov_b32_e32 v165, v83
	v_pk_add_f32 v[158:159], v[158:159], v[160:161]
	v_pk_add_f32 v[160:161], v[162:163], v[164:165]
	v_add_f32_e32 v167, v30, v31
	v_mov_b32_e32 v166, v1
	v_mov_b32_e32 v168, v3
	s_waitcnt vmcnt(15)
	v_pk_fma_f32 v[126:127], v[188:189], s[4:5], v[126:127] op_sel_hi:[1,0,1]
	v_pk_fma_f32 v[124:125], v[186:187], s[4:5], v[124:125] op_sel_hi:[1,0,1]
	s_waitcnt vmcnt(14)
	v_pk_fma_f32 v[86:87], v[192:193], s[4:5], v[86:87] op_sel_hi:[1,0,1]
	v_pk_fma_f32 v[84:85], v[190:191], s[4:5], v[84:85] op_sel_hi:[1,0,1]
	s_waitcnt vmcnt(13)
	v_pk_fma_f32 v[42:43], v[196:197], s[4:5], v[42:43] op_sel_hi:[1,0,1]
	v_pk_fma_f32 v[40:41], v[194:195], s[4:5], v[40:41] op_sel_hi:[1,0,1]
	s_waitcnt vmcnt(12)
	v_pk_fma_f32 v[6:7], v[200:201], s[4:5], v[6:7] op_sel_hi:[1,0,1]
	v_pk_fma_f32 v[4:5], v[198:199], s[4:5], v[4:5] op_sel_hi:[1,0,1]
	s_nop 0
	s_mov_b32 s98, 0x90000
	v_lshl_add_u64 v[226:227], v[238:239], 0, s[98:99]
	global_load_dwordx4 v[186:189], v[226:227], off
	global_load_dwordx4 v[190:193], v[226:227], off offset:64
	global_load_dwordx4 v[194:197], v[226:227], off offset:512
	global_load_dwordx4 v[198:201], v[226:227], off offset:576
	v_or_b32_e32 v134, 48, v128
	v_ashrrev_i32_e32 v135, 31, v134
	v_lshlrev_b64 v[134:135], 12, v[134:135]
	v_lshl_add_u64 v[134:135], s[38:39], 0, v[134:135]
	v_lshl_add_u64 v[134:135], v[134:135], 0, v[132:133]
	s_waitcnt vmcnt(15)
	v_pk_fma_f32 v[122:123], v[204:205], s[4:5], v[122:123] op_sel_hi:[1,0,1]
	v_pk_fma_f32 v[120:121], v[202:203], s[4:5], v[120:121] op_sel_hi:[1,0,1]
	s_waitcnt vmcnt(14)
	v_pk_fma_f32 v[98:99], v[208:209], s[4:5], v[98:99] op_sel_hi:[1,0,1]
	v_pk_fma_f32 v[96:97], v[206:207], s[4:5], v[96:97] op_sel_hi:[1,0,1]
	s_waitcnt vmcnt(13)
	v_pk_fma_f32 v[46:47], v[212:213], s[4:5], v[46:47] op_sel_hi:[1,0,1]
	v_pk_fma_f32 v[44:45], v[210:211], s[4:5], v[44:45] op_sel_hi:[1,0,1]
	s_waitcnt vmcnt(12)
	v_pk_fma_f32 v[10:11], v[216:217], s[4:5], v[10:11] op_sel_hi:[1,0,1]
	v_pk_fma_f32 v[8:9], v[214:215], s[4:5], v[8:9] op_sel_hi:[1,0,1]
	s_nop 0
	s_mov_b32 s98, 0xa0000
	v_lshl_add_u64 v[226:227], v[238:239], 0, s[98:99]
	global_load_dwordx4 v[202:205], v[226:227], off
	global_load_dwordx4 v[206:209], v[226:227], off offset:64
	global_load_dwordx4 v[210:213], v[226:227], off offset:512
	global_load_dwordx4 v[214:217], v[226:227], off offset:576
	v_add_u32_e32 v134, 0x80, v128
	v_ashrrev_i32_e32 v135, 31, v134
	v_lshlrev_b64 v[134:135], 12, v[134:135]
	v_lshl_add_u64 v[134:135], s[38:39], 0, v[134:135]
	v_lshl_add_u64 v[134:135], v[134:135], 0, v[132:133]
	s_waitcnt vmcnt(15)
	v_pk_fma_f32 v[114:115], v[220:221], s[4:5], v[114:115] op_sel_hi:[1,0,1]
	v_pk_fma_f32 v[112:113], v[218:219], s[4:5], v[112:113] op_sel_hi:[1,0,1]
	s_waitcnt vmcnt(14)
	v_pk_fma_f32 v[102:103], v[224:225], s[4:5], v[102:103] op_sel_hi:[1,0,1]
	v_pk_fma_f32 v[100:101], v[222:223], s[4:5], v[100:101] op_sel_hi:[1,0,1]
	s_waitcnt vmcnt(13)
	v_pk_fma_f32 v[58:59], v[232:233], s[4:5], v[58:59] op_sel_hi:[1,0,1]
	v_pk_fma_f32 v[56:57], v[230:231], s[4:5], v[56:57] op_sel_hi:[1,0,1]
	s_waitcnt vmcnt(12)
	v_pk_fma_f32 v[14:15], v[236:237], s[4:5], v[14:15] op_sel_hi:[1,0,1]
	v_pk_fma_f32 v[12:13], v[234:235], s[4:5], v[12:13] op_sel_hi:[1,0,1]
	s_nop 0
	s_mov_b32 s98, 0xb0000
	v_lshl_add_u64 v[226:227], v[238:239], 0, s[98:99]
	global_load_dwordx4 v[218:221], v[226:227], off
	global_load_dwordx4 v[222:225], v[226:227], off offset:64
	global_load_dwordx4 v[230:233], v[226:227], off offset:512
	global_load_dwordx4 v[234:237], v[226:227], off offset:576
	v_add_u32_e32 v134, 0x90, v128
	v_ashrrev_i32_e32 v135, 31, v134
	v_lshlrev_b64 v[134:135], 12, v[134:135]
	v_lshl_add_u64 v[134:135], s[38:39], 0, v[134:135]
	v_lshl_add_u64 v[134:135], v[134:135], 0, v[132:133]
	s_waitcnt vmcnt(15)
	v_pk_fma_f32 v[110:111], v[172:173], s[4:5], v[110:111] op_sel_hi:[1,0,1]
	v_pk_fma_f32 v[108:109], v[170:171], s[4:5], v[108:109] op_sel_hi:[1,0,1]
	s_waitcnt vmcnt(14)
	v_pk_fma_f32 v[106:107], v[176:177], s[4:5], v[106:107] op_sel_hi:[1,0,1]
	v_pk_fma_f32 v[104:105], v[174:175], s[4:5], v[104:105] op_sel_hi:[1,0,1]
	s_waitcnt vmcnt(13)
	v_pk_fma_f32 v[62:63], v[180:181], s[4:5], v[62:63] op_sel_hi:[1,0,1]
	v_pk_fma_f32 v[60:61], v[178:179], s[4:5], v[60:61] op_sel_hi:[1,0,1]
	s_waitcnt vmcnt(12)
	v_pk_fma_f32 v[18:19], v[184:185], s[4:5], v[18:19] op_sel_hi:[1,0,1]
	v_pk_fma_f32 v[16:17], v[182:183], s[4:5], v[16:17] op_sel_hi:[1,0,1]
	s_nop 0
	v_add_u32_e32 v134, 0xa0, v128
	v_ashrrev_i32_e32 v135, 31, v134
	v_lshlrev_b64 v[134:135], 12, v[134:135]
	v_lshl_add_u64 v[134:135], s[38:39], 0, v[134:135]
	v_lshl_add_u64 v[134:135], v[134:135], 0, v[132:133]
	s_waitcnt vmcnt(11)
	v_pk_fma_f32 v[94:95], v[188:189], s[4:5], v[94:95] op_sel_hi:[1,0,1]
	v_pk_fma_f32 v[92:93], v[186:187], s[4:5], v[92:93] op_sel_hi:[1,0,1]
	s_waitcnt vmcnt(10)
	v_pk_fma_f32 v[90:91], v[192:193], s[4:5], v[90:91] op_sel_hi:[1,0,1]
	v_pk_fma_f32 v[88:89], v[190:191], s[4:5], v[88:89] op_sel_hi:[1,0,1]
	s_waitcnt vmcnt(9)
	v_pk_fma_f32 v[70:71], v[196:197], s[4:5], v[70:71] op_sel_hi:[1,0,1]
	v_pk_fma_f32 v[68:69], v[194:195], s[4:5], v[68:69] op_sel_hi:[1,0,1]
	s_waitcnt vmcnt(8)
	v_pk_fma_f32 v[22:23], v[200:201], s[4:5], v[22:23] op_sel_hi:[1,0,1]
	v_pk_fma_f32 v[20:21], v[198:199], s[4:5], v[20:21] op_sel_hi:[1,0,1]
	s_nop 0
	v_add_u32_e32 v134, 0xb0, v128
	v_ashrrev_i32_e32 v135, 31, v134
	v_lshlrev_b64 v[134:135], 12, v[134:135]
	v_lshl_add_u64 v[134:135], s[38:39], 0, v[134:135]
	v_lshl_add_u64 v[134:135], v[134:135], 0, v[132:133]
	v_add_f32_e32 v128, v158, v159
	v_pk_add_f32 v[158:159], v[160:161], v[160:161] op_sel_hi:[0,1]
	v_add_f32_e32 v169, 0, v128
	v_mov_b32_e32 v158, v2
	v_pk_add_f32 v[158:159], v[158:159], v[168:169]
	v_xor_b32_e32 v128, 32, v144
	v_cmp_lt_i32_e32 vcc, v128, v131
	s_waitcnt vmcnt(7)
	v_pk_fma_f32 v[78:79], v[204:205], s[4:5], v[78:79] op_sel_hi:[1,0,1]
	v_pk_fma_f32 v[76:77], v[202:203], s[4:5], v[76:77] op_sel_hi:[1,0,1]
	s_waitcnt vmcnt(6)
	v_pk_fma_f32 v[74:75], v[208:209], s[4:5], v[74:75] op_sel_hi:[1,0,1]
	v_pk_fma_f32 v[72:73], v[206:207], s[4:5], v[72:73] op_sel_hi:[1,0,1]
	s_waitcnt vmcnt(5)
	v_pk_fma_f32 v[66:67], v[212:213], s[4:5], v[66:67] op_sel_hi:[1,0,1]
	v_pk_fma_f32 v[64:65], v[210:211], s[4:5], v[64:65] op_sel_hi:[1,0,1]
	s_waitcnt vmcnt(4)
	v_pk_fma_f32 v[26:27], v[216:217], s[4:5], v[26:27] op_sel_hi:[1,0,1]
	v_pk_fma_f32 v[24:25], v[214:215], s[4:5], v[24:25] op_sel_hi:[1,0,1]
	v_cndmask_b32_e32 v128, v144, v128, vcc
	v_add_f32_e32 v135, v28, v29
	v_mov_b32_e32 v134, v0
	v_pk_add_f32 v[134:135], v[134:135], v[166:167]
	v_lshlrev_b32_e32 v128, 2, v128
	v_pk_add_f32 v[134:135], v[134:135], v[158:159]
	v_cmp_gt_u32_e32 vcc, 16, v130
	v_add_f32_e32 v134, v134, v135
	ds_bpermute_b32 v135, v129, v134
	s_waitcnt lgkmcnt(0)
	v_add_f32_e32 v131, v134, v135
	ds_bpermute_b32 v134, v128, v131
	s_waitcnt lgkmcnt(0)
	v_add_f32_e32 v131, v131, v134
	v_fmamk_f32 v135, v131, 0xbc800000, v119
	v_fmamk_f32 v144, v131, 0xbc800000, v117
	v_fmamk_f32 v158, v131, 0xbc800000, v83
	v_fmamk_f32 v160, v131, 0xbc800000, v81
	v_fmamk_f32 v134, v131, 0xbc800000, v118
	v_fmamk_f32 v139, v131, 0xbc800000, v116
	v_fmamk_f32 v145, v131, 0xbc800000, v82
	v_fmamk_f32 v159, v131, 0xbc800000, v80
	v_fmamk_f32 v162, v131, 0xbc800000, v31
	v_fmamk_f32 v164, v131, 0xbc800000, v29
	v_mul_f32_e32 v144, v144, v144
	v_mul_f32_e32 v135, v135, v135
	v_mul_f32_e32 v160, v160, v160
	v_mul_f32_e32 v158, v158, v158
	v_fmamk_f32 v161, v131, 0xbc800000, v30
	v_fmamk_f32 v163, v131, 0xbc800000, v28
	v_fmamk_f32 v166, v131, 0xbc800000, v3
	v_fmamk_f32 v168, v131, 0xbc800000, v1
	v_mul_f32_e32 v164, v164, v164
	v_mul_f32_e32 v162, v162, v162
	v_fmac_f32_e32 v144, v139, v139
	v_fmac_f32_e32 v135, v134, v134
	v_fmac_f32_e32 v160, v159, v159
	v_fmac_f32_e32 v158, v145, v145
	v_fmamk_f32 v165, v131, 0xbc800000, v2
	v_fmamk_f32 v167, v131, 0xbc800000, v0
	v_mul_f32_e32 v168, v168, v168
	v_mul_f32_e32 v166, v166, v166
	v_fmac_f32_e32 v164, v163, v163
	v_fmac_f32_e32 v162, v161, v161
	v_add_f32_e32 v134, v144, v135
	v_add_f32_e32 v135, v160, v158
	v_fmac_f32_e32 v168, v167, v167
	v_fmac_f32_e32 v166, v165, v165
	v_add_f32_e32 v139, v164, v162
	v_add_f32_e32 v134, v134, v135
	v_add_f32_e32 v144, v168, v166
	v_add_f32_e32 v134, v139, v134
	v_add_f32_e32 v134, v144, v134
	ds_bpermute_b32 v135, v129, v134
	s_waitcnt lgkmcnt(0)
	v_add_f32_e32 v134, v134, v135
	ds_bpermute_b32 v135, v128, v134
	s_waitcnt vmcnt(3)
	v_pk_fma_f32 v[54:55], v[220:221], s[4:5], v[54:55] op_sel_hi:[1,0,1]
	v_pk_fma_f32 v[52:53], v[218:219], s[4:5], v[52:53] op_sel_hi:[1,0,1]
	s_waitcnt vmcnt(2)
	v_pk_fma_f32 v[50:51], v[224:225], s[4:5], v[50:51] op_sel_hi:[1,0,1]
	v_pk_fma_f32 v[48:49], v[222:223], s[4:5], v[48:49] op_sel_hi:[1,0,1]
	s_waitcnt vmcnt(1)
	v_pk_fma_f32 v[38:39], v[232:233], s[4:5], v[38:39] op_sel_hi:[1,0,1]
	v_pk_fma_f32 v[36:37], v[230:231], s[4:5], v[36:37] op_sel_hi:[1,0,1]
	s_waitcnt vmcnt(0)
	v_pk_fma_f32 v[34:35], v[236:237], s[4:5], v[34:35] op_sel_hi:[1,0,1]
	v_pk_fma_f32 v[32:33], v[234:235], s[4:5], v[32:33] op_sel_hi:[1,0,1]
	s_nop 0
	s_and_saveexec_b64 s[4:5], vcc
	v_readlane_b32 s28, v244, 7
	v_readlane_b32 s24, v244, 9
	v_readlane_b32 s29, v244, 8
	v_readlane_b32 s25, v244, 10
	s_cbranch_execz .LBB0_977
	s_lshl_b32 s6, s1, 11
	s_add_i32 s6, s2, s6
	v_mul_f32_e32 v140, 0x3c800000, v131
	v_lshl_add_u32 v131, v130, 5, s6
	s_waitcnt lgkmcnt(0)
	v_add_f32_e32 v141, v134, v135
	ds_write_b64 v131, v[140:141]

.LBB0_1232:
	v_mov_b32_e32 v130, v154
	s_lshl_b32 s4, s3, 5
	s_barrier
	s_lshl_b32 s5, s34, 8
	v_ashrrev_i32_e32 v128, 2, v130
	s_or_b32 s4, s5, s4
	v_and_b32_e32 v128, -4, v128
	s_lshl_b32 s20, s1, 8
	v_and_b32_e32 v158, 15, v130
	v_add_u32_e32 v136, s4, v128
	s_add_i32 s4, s20, s0
	v_or_b32_e32 v128, s4, v158
	v_ashrrev_i32_e32 v129, 31, v128
	v_ashrrev_i32_e32 v137, 31, v136
	v_lshlrev_b64 v[132:133], 12, v[128:129]
	v_lshl_add_u64 v[134:135], s[16:17], 0, v[132:133]
	v_lshlrev_b64 v[132:133], 2, v[136:137]
	v_lshl_add_u64 v[138:139], v[134:135], 0, v[132:133]
	v_mov_b32_e32 v238, v138
	v_mov_b32_e32 v239, v139
	s_mov_b32 s99, 0
	global_load_dwordx4 v[186:189], v[138:139], off
	global_load_dwordx4 v[190:193], v[138:139], off offset:64
	global_load_dwordx4 v[194:197], v[138:139], off offset:512
	global_load_dwordx4 v[198:201], v[138:139], off offset:576
	s_mov_b32 s98, 0x10000
	v_lshl_add_u64 v[226:227], v[238:239], 0, s[98:99]
	global_load_dwordx4 v[202:205], v[226:227], off
	global_load_dwordx4 v[206:209], v[226:227], off offset:64
	global_load_dwordx4 v[210:213], v[226:227], off offset:512
	global_load_dwordx4 v[214:217], v[226:227], off offset:576
	s_mov_b32 s98, 0x20000
	v_lshl_add_u64 v[226:227], v[238:239], 0, s[98:99]
	global_load_dwordx4 v[218:221], v[226:227], off
	global_load_dwordx4 v[222:225], v[226:227], off offset:64
	global_load_dwordx4 v[230:233], v[226:227], off offset:512
	global_load_dwordx4 v[234:237], v[226:227], off offset:576
	v_or_b32_e32 v134, 16, v128
	v_ashrrev_i32_e32 v135, 31, v134
	v_lshlrev_b64 v[134:135], 12, v[134:135]
	s_mov_b32 s4, 0x3fb504f3
	v_lshl_add_u64 v[134:135], s[16:17], 0, v[134:135]
	v_lshl_add_u64 v[140:141], v[134:135], 0, v[132:133]
	v_or_b32_e32 v134, 32, v128
	v_ashrrev_i32_e32 v135, 31, v134
	v_lshlrev_b64 v[134:135], 12, v[134:135]
	v_lshl_add_u64 v[134:135], s[16:17], 0, v[134:135]
	v_and_b32_e32 v131, 64, v154
	v_xor_b32_e32 v129, 16, v154
	v_add_u32_e32 v131, 64, v131
	v_cmp_lt_i32_e32 vcc, v129, v131
	s_lshl_b32 s3, s3, 3
	s_add_i32 s3, s3, 0
	v_cndmask_b32_e32 v129, v154, v129, vcc
	v_lshlrev_b32_e32 v129, 2, v129
	s_waitcnt vmcnt(8)
	v_pk_fma_f32 v[114:115], v[188:189], s[4:5], v[114:115] op_sel_hi:[1,0,1]
	v_pk_fma_f32 v[112:113], v[186:187], s[4:5], v[112:113] op_sel_hi:[1,0,1]
	v_pk_fma_f32 v[86:87], v[192:193], s[4:5], v[86:87] op_sel_hi:[1,0,1]
	v_pk_fma_f32 v[84:85], v[190:191], s[4:5], v[84:85] op_sel_hi:[1,0,1]
	v_pk_fma_f32 v[42:43], v[196:197], s[4:5], v[42:43] op_sel_hi:[1,0,1]
	v_pk_fma_f32 v[40:41], v[194:195], s[4:5], v[40:41] op_sel_hi:[1,0,1]
	v_pk_fma_f32 v[2:3], v[200:201], s[4:5], v[2:3] op_sel_hi:[1,0,1]
	v_pk_fma_f32 v[0:1], v[198:199], s[4:5], v[0:1] op_sel_hi:[1,0,1]
	v_lshl_add_u64 v[142:143], v[134:135], 0, v[132:133]
	s_mov_b32 s98, 0x30000
	v_lshl_add_u64 v[226:227], v[238:239], 0, s[98:99]
	global_load_dwordx4 v[186:189], v[226:227], off
	global_load_dwordx4 v[190:193], v[226:227], off offset:64
	global_load_dwordx4 v[194:197], v[226:227], off offset:512
	global_load_dwordx4 v[198:201], v[226:227], off offset:576
	v_or_b32_e32 v134, 48, v128
	v_ashrrev_i32_e32 v135, 31, v134
	v_lshlrev_b64 v[134:135], 12, v[134:135]
	v_lshl_add_u64 v[134:135], s[16:17], 0, v[134:135]
	v_mov_b32_e32 v156, v112
	v_mov_b32_e32 v157, v115
	v_mov_b32_e32 v176, v85
	v_mov_b32_e32 v177, v86
	v_mov_b32_e32 v178, v84
	v_mov_b32_e32 v179, v87
	v_add_f32_e32 v181, v40, v41
	v_add_f32_e32 v183, v42, v43
	v_mov_b32_e32 v180, v0
	v_mov_b32_e32 v182, v1
	v_mov_b32_e32 v184, v3
	s_waitcnt vmcnt(11)
	v_pk_fma_f32 v[122:123], v[204:205], s[4:5], v[122:123] op_sel_hi:[1,0,1]
	v_pk_fma_f32 v[120:121], v[202:203], s[4:5], v[120:121] op_sel_hi:[1,0,1]
	s_waitcnt vmcnt(10)
	v_pk_fma_f32 v[94:95], v[208:209], s[4:5], v[94:95] op_sel_hi:[1,0,1]
	v_pk_fma_f32 v[92:93], v[206:207], s[4:5], v[92:93] op_sel_hi:[1,0,1]
	s_waitcnt vmcnt(9)
	v_pk_fma_f32 v[54:55], v[212:213], s[4:5], v[54:55] op_sel_hi:[1,0,1]
	v_pk_fma_f32 v[52:53], v[210:211], s[4:5], v[52:53] op_sel_hi:[1,0,1]
	s_waitcnt vmcnt(8)
	v_pk_fma_f32 v[6:7], v[216:217], s[4:5], v[6:7] op_sel_hi:[1,0,1]
	v_pk_fma_f32 v[4:5], v[214:215], s[4:5], v[4:5] op_sel_hi:[1,0,1]
	v_lshl_add_u64 v[144:145], v[134:135], 0, v[132:133]
	s_mov_b32 s98, 0x80000
	v_lshl_add_u64 v[226:227], v[238:239], 0, s[98:99]
	global_load_dwordx4 v[202:205], v[226:227], off
	global_load_dwordx4 v[206:209], v[226:227], off offset:64
	global_load_dwordx4 v[210:213], v[226:227], off offset:512
	global_load_dwordx4 v[214:217], v[226:227], off offset:576
	v_add_u32_e32 v134, 0x80, v128
	v_ashrrev_i32_e32 v135, 31, v134
	v_lshlrev_b64 v[134:135], 12, v[134:135]
	v_lshl_add_u64 v[134:135], s[16:17], 0, v[134:135]
	s_waitcnt vmcnt(11)
	v_pk_fma_f32 v[126:127], v[220:221], s[4:5], v[126:127] op_sel_hi:[1,0,1]
	v_pk_fma_f32 v[124:125], v[218:219], s[4:5], v[124:125] op_sel_hi:[1,0,1]
	s_waitcnt vmcnt(10)
	v_pk_fma_f32 v[98:99], v[224:225], s[4:5], v[98:99] op_sel_hi:[1,0,1]
	v_pk_fma_f32 v[96:97], v[222:223], s[4:5], v[96:97] op_sel_hi:[1,0,1]
	s_waitcnt vmcnt(9)
	v_pk_fma_f32 v[58:59], v[232:233], s[4:5], v[58:59] op_sel_hi:[1,0,1]
	v_pk_fma_f32 v[56:57], v[230:231], s[4:5], v[56:57] op_sel_hi:[1,0,1]
	s_waitcnt vmcnt(8)
	v_pk_fma_f32 v[10:11], v[236:237], s[4:5], v[10:11] op_sel_hi:[1,0,1]
	v_pk_fma_f32 v[8:9], v[234:235], s[4:5], v[8:9] op_sel_hi:[1,0,1]
	v_lshl_add_u64 v[146:147], v[134:135], 0, v[132:133]
	s_mov_b32 s98, 0x90000
	v_lshl_add_u64 v[226:227], v[238:239], 0, s[98:99]
	global_load_dwordx4 v[218:221], v[226:227], off
	global_load_dwordx4 v[222:225], v[226:227], off offset:64
	global_load_dwordx4 v[230:233], v[226:227], off offset:512
	global_load_dwordx4 v[234:237], v[226:227], off offset:576
	v_add_u32_e32 v134, 0x90, v128
	v_ashrrev_i32_e32 v135, 31, v134
	v_lshlrev_b64 v[134:135], 12, v[134:135]
	v_lshl_add_u64 v[134:135], s[16:17], 0, v[134:135]
	s_waitcnt vmcnt(11)
	v_pk_fma_f32 v[118:119], v[188:189], s[4:5], v[118:119] op_sel_hi:[1,0,1]
	v_pk_fma_f32 v[116:117], v[186:187], s[4:5], v[116:117] op_sel_hi:[1,0,1]
	s_waitcnt vmcnt(10)
	v_pk_fma_f32 v[110:111], v[192:193], s[4:5], v[110:111] op_sel_hi:[1,0,1]
	v_pk_fma_f32 v[108:109], v[190:191], s[4:5], v[108:109] op_sel_hi:[1,0,1]
	s_waitcnt vmcnt(9)
	v_pk_fma_f32 v[70:71], v[196:197], s[4:5], v[70:71] op_sel_hi:[1,0,1]
	v_pk_fma_f32 v[68:69], v[194:195], s[4:5], v[68:69] op_sel_hi:[1,0,1]
	s_waitcnt vmcnt(8)
	v_pk_fma_f32 v[14:15], v[200:201], s[4:5], v[14:15] op_sel_hi:[1,0,1]
	v_pk_fma_f32 v[12:13], v[198:199], s[4:5], v[12:13] op_sel_hi:[1,0,1]
	v_lshl_add_u64 v[148:149], v[134:135], 0, v[132:133]
	s_mov_b32 s98, 0xa0000
	v_lshl_add_u64 v[226:227], v[238:239], 0, s[98:99]
	global_load_dwordx4 v[186:189], v[226:227], off
	global_load_dwordx4 v[190:193], v[226:227], off offset:64
	global_load_dwordx4 v[194:197], v[226:227], off offset:512
	global_load_dwordx4 v[198:201], v[226:227], off offset:576
	v_add_u32_e32 v134, 0xa0, v128
	v_ashrrev_i32_e32 v135, 31, v134
	v_lshlrev_b64 v[134:135], 12, v[134:135]
	v_lshl_add_u64 v[134:135], s[16:17], 0, v[134:135]
	s_waitcnt vmcnt(11)
	v_pk_fma_f32 v[106:107], v[204:205], s[4:5], v[106:107] op_sel_hi:[1,0,1]
	v_pk_fma_f32 v[104:105], v[202:203], s[4:5], v[104:105] op_sel_hi:[1,0,1]
	s_waitcnt vmcnt(10)
	v_pk_fma_f32 v[102:103], v[208:209], s[4:5], v[102:103] op_sel_hi:[1,0,1]
	v_pk_fma_f32 v[100:101], v[206:207], s[4:5], v[100:101] op_sel_hi:[1,0,1]
	s_waitcnt vmcnt(9)
	v_pk_fma_f32 v[74:75], v[212:213], s[4:5], v[74:75] op_sel_hi:[1,0,1]
	v_pk_fma_f32 v[72:73], v[210:211], s[4:5], v[72:73] op_sel_hi:[1,0,1]
	s_waitcnt vmcnt(8)
	v_pk_fma_f32 v[26:27], v[216:217], s[4:5], v[26:27] op_sel_hi:[1,0,1]
	v_pk_fma_f32 v[24:25], v[214:215], s[4:5], v[24:25] op_sel_hi:[1,0,1]
	v_lshl_add_u64 v[150:151], v[134:135], 0, v[132:133]
	s_mov_b32 s98, 0xb0000
	v_lshl_add_u64 v[226:227], v[238:239], 0, s[98:99]
	global_load_dwordx4 v[202:205], v[226:227], off
	global_load_dwordx4 v[206:209], v[226:227], off offset:64
	global_load_dwordx4 v[210:213], v[226:227], off offset:512
	global_load_dwordx4 v[214:217], v[226:227], off offset:576
	v_add_u32_e32 v134, 0xb0, v128
	v_ashrrev_i32_e32 v135, 31, v134
	v_lshlrev_b64 v[134:135], 12, v[134:135]
	v_lshl_add_u64 v[134:135], s[16:17], 0, v[134:135]
	v_lshl_add_u64 v[152:153], v[134:135], 0, v[132:133]
	v_mov_b32_e32 v134, v113
	v_mov_b32_e32 v135, v114
	v_pk_add_f32 v[134:135], v[134:135], v[156:157]
	v_pk_add_f32 v[156:157], v[176:177], v[178:179]
	v_add_f32_e32 v128, v134, v135
	v_pk_add_f32 v[134:135], v[156:157], v[156:157] op_sel_hi:[0,1]
	v_add_f32_e32 v185, 0, v128
	v_mov_b32_e32 v134, v2
	v_pk_add_f32 v[176:177], v[180:181], v[182:183]
	v_pk_add_f32 v[134:135], v[134:135], v[184:185]
	v_xor_b32_e32 v128, 32, v154
	v_pk_add_f32 v[134:135], v[176:177], v[134:135]
	v_cmp_lt_i32_e32 vcc, v128, v131
	v_add_f32_e32 v134, v134, v135
	ds_bpermute_b32 v135, v129, v134
	v_cndmask_b32_e32 v128, v154, v128, vcc
	v_lshlrev_b32_e32 v128, 2, v128
	v_cmp_gt_u32_e32 vcc, 16, v130
	s_waitcnt lgkmcnt(0)
	v_add_f32_e32 v131, v134, v135
	ds_bpermute_b32 v134, v128, v131
	s_waitcnt lgkmcnt(0)
	v_add_f32_e32 v131, v131, v134
	v_fmamk_f32 v135, v131, 0xbc800000, v115
	v_fmamk_f32 v155, v131, 0xbc800000, v113
	v_fmamk_f32 v157, v131, 0xbc800000, v87
	v_fmamk_f32 v176, v131, 0xbc800000, v85
	v_fmamk_f32 v134, v131, 0xbc800000, v114
	v_fmamk_f32 v154, v131, 0xbc800000, v112
	v_fmamk_f32 v156, v131, 0xbc800000, v86
	v_fmamk_f32 v159, v131, 0xbc800000, v84
	v_fmamk_f32 v178, v131, 0xbc800000, v43
	v_fmamk_f32 v180, v131, 0xbc800000, v41
	v_mul_f32_e32 v155, v155, v155
	v_mul_f32_e32 v135, v135, v135
	v_mul_f32_e32 v176, v176, v176
	v_mul_f32_e32 v157, v157, v157
	v_fmamk_f32 v177, v131, 0xbc800000, v42
	v_fmamk_f32 v179, v131, 0xbc800000, v40
	v_fmamk_f32 v182, v131, 0xbc800000, v3
	v_fmamk_f32 v184, v131, 0xbc800000, v1
	v_mul_f32_e32 v180, v180, v180
	v_mul_f32_e32 v178, v178, v178
	v_fmac_f32_e32 v155, v154, v154
	v_fmac_f32_e32 v135, v134, v134
	v_fmac_f32_e32 v176, v159, v159
	v_fmac_f32_e32 v157, v156, v156
	v_fmamk_f32 v181, v131, 0xbc800000, v2
	v_fmamk_f32 v183, v131, 0xbc800000, v0
	v_mul_f32_e32 v184, v184, v184
	v_mul_f32_e32 v182, v182, v182
	v_fmac_f32_e32 v180, v179, v179
	v_fmac_f32_e32 v178, v177, v177
	v_add_f32_e32 v134, v155, v135
	v_add_f32_e32 v135, v176, v157
	v_fmac_f32_e32 v184, v183, v183
	v_fmac_f32_e32 v182, v181, v181
	v_add_f32_e32 v154, v180, v178
	v_add_f32_e32 v134, v134, v135
	v_add_f32_e32 v155, v184, v182
	v_add_f32_e32 v134, v154, v134
	v_add_f32_e32 v134, v155, v134
	ds_bpermute_b32 v135, v129, v134
	s_waitcnt lgkmcnt(0)
	v_add_f32_e32 v134, v134, v135
	s_waitcnt vmcnt(11)
	v_pk_fma_f32 v[90:91], v[220:221], s[4:5], v[90:91] op_sel_hi:[1,0,1]
	v_pk_fma_f32 v[88:89], v[218:219], s[4:5], v[88:89] op_sel_hi:[1,0,1]
	s_waitcnt vmcnt(10)
	v_pk_fma_f32 v[82:83], v[224:225], s[4:5], v[82:83] op_sel_hi:[1,0,1]
	v_pk_fma_f32 v[80:81], v[222:223], s[4:5], v[80:81] op_sel_hi:[1,0,1]
	s_waitcnt vmcnt(9)
	v_pk_fma_f32 v[78:79], v[232:233], s[4:5], v[78:79] op_sel_hi:[1,0,1]
	v_pk_fma_f32 v[76:77], v[230:231], s[4:5], v[76:77] op_sel_hi:[1,0,1]
	s_waitcnt vmcnt(8)
	v_pk_fma_f32 v[30:31], v[236:237], s[4:5], v[30:31] op_sel_hi:[1,0,1]
	v_pk_fma_f32 v[28:29], v[234:235], s[4:5], v[28:29] op_sel_hi:[1,0,1]
	ds_bpermute_b32 v135, v128, v134
	s_waitcnt vmcnt(7)
	v_pk_fma_f32 v[66:67], v[188:189], s[4:5], v[66:67] op_sel_hi:[1,0,1]
	v_pk_fma_f32 v[64:65], v[186:187], s[4:5], v[64:65] op_sel_hi:[1,0,1]
	s_waitcnt vmcnt(6)
	v_pk_fma_f32 v[62:63], v[192:193], s[4:5], v[62:63] op_sel_hi:[1,0,1]
	v_pk_fma_f32 v[60:61], v[190:191], s[4:5], v[60:61] op_sel_hi:[1,0,1]
	s_waitcnt vmcnt(5)
	v_pk_fma_f32 v[50:51], v[196:197], s[4:5], v[50:51] op_sel_hi:[1,0,1]
	v_pk_fma_f32 v[48:49], v[194:195], s[4:5], v[48:49] op_sel_hi:[1,0,1]
	s_waitcnt vmcnt(4)
	v_pk_fma_f32 v[46:47], v[200:201], s[4:5], v[46:47] op_sel_hi:[1,0,1]
	v_pk_fma_f32 v[44:45], v[198:199], s[4:5], v[44:45] op_sel_hi:[1,0,1]
	s_nop 0
	s_waitcnt vmcnt(3)
	v_pk_fma_f32 v[38:39], v[204:205], s[4:5], v[38:39] op_sel_hi:[1,0,1]
	v_pk_fma_f32 v[36:37], v[202:203], s[4:5], v[36:37] op_sel_hi:[1,0,1]
	s_waitcnt vmcnt(2)
	v_pk_fma_f32 v[34:35], v[208:209], s[4:5], v[34:35] op_sel_hi:[1,0,1]
	v_pk_fma_f32 v[32:33], v[206:207], s[4:5], v[32:33] op_sel_hi:[1,0,1]
	s_waitcnt vmcnt(1)
	v_pk_fma_f32 v[22:23], v[212:213], s[4:5], v[22:23] op_sel_hi:[1,0,1]
	v_pk_fma_f32 v[20:21], v[210:211], s[4:5], v[20:21] op_sel_hi:[1,0,1]
	s_waitcnt vmcnt(0)
	v_pk_fma_f32 v[18:19], v[216:217], s[4:5], v[18:19] op_sel_hi:[1,0,1]
	v_pk_fma_f32 v[16:17], v[214:215], s[4:5], v[16:17] op_sel_hi:[1,0,1]
	s_nop 0
	s_and_saveexec_b64 s[4:5], vcc
	v_readlane_b32 s28, v244, 7
	v_readlane_b32 s24, v244, 9
	v_readlane_b32 s29, v244, 8
	v_readlane_b32 s25, v244, 10
	s_cbranch_execz .LBB0_1234
	s_lshl_b32 s6, s2, 11
	s_add_i32 s6, s3, s6
	v_mul_f32_e32 v154, 0x3c800000, v131
	v_lshl_add_u32 v131, v130, 5, s6
	s_waitcnt lgkmcnt(0)
	v_add_f32_e32 v155, v134, v135
	ds_write_b64 v131, v[154:155]

.LBB0_1561:
	v_mov_b32_e32 v130, v154
	s_lshl_b32 s3, s2, 5
	s_barrier
	s_lshl_b32 s4, s36, 8
	v_ashrrev_i32_e32 v128, 2, v130
	s_or_b32 s3, s4, s3
	v_and_b32_e32 v128, -4, v128
	v_add_u32_e32 v138, s3, v128
	s_lshl_b32 s3, s34, 8
	v_and_b32_e32 v155, 15, v130
	s_add_i32 s4, s3, s0
	v_or_b32_e32 v128, s4, v155
	v_ashrrev_i32_e32 v129, 31, v128
	v_ashrrev_i32_e32 v139, 31, v138
	v_lshlrev_b64 v[132:133], 12, v[128:129]
	v_lshl_add_u64 v[134:135], s[8:9], 0, v[132:133]
	v_lshlrev_b64 v[132:133], 2, v[138:139]
	v_lshl_add_u64 v[136:137], v[134:135], 0, v[132:133]
	v_mov_b32_e32 v238, v136
	v_mov_b32_e32 v239, v137
	s_mov_b32 s99, 0
	global_load_dwordx4 v[186:189], v[136:137], off
	global_load_dwordx4 v[190:193], v[136:137], off offset:64
	global_load_dwordx4 v[194:197], v[136:137], off offset:512
	global_load_dwordx4 v[198:201], v[136:137], off offset:576
	s_mov_b32 s98, 0x10000
	v_lshl_add_u64 v[226:227], v[238:239], 0, s[98:99]
	global_load_dwordx4 v[202:205], v[226:227], off
	global_load_dwordx4 v[206:209], v[226:227], off offset:64
	global_load_dwordx4 v[210:213], v[226:227], off offset:512
	global_load_dwordx4 v[214:217], v[226:227], off offset:576
	s_mov_b32 s98, 0x20000
	v_lshl_add_u64 v[226:227], v[238:239], 0, s[98:99]
	global_load_dwordx4 v[218:221], v[226:227], off
	global_load_dwordx4 v[222:225], v[226:227], off offset:64
	global_load_dwordx4 v[230:233], v[226:227], off offset:512
	global_load_dwordx4 v[234:237], v[226:227], off offset:576
	v_or_b32_e32 v134, 16, v128
	v_ashrrev_i32_e32 v135, 31, v134
	v_lshlrev_b64 v[134:135], 12, v[134:135]
	s_mov_b32 s4, 0x3fb504f3
	v_lshl_add_u64 v[134:135], s[8:9], 0, v[134:135]
	v_lshl_add_u64 v[140:141], v[134:135], 0, v[132:133]
	v_or_b32_e32 v134, 32, v128
	v_ashrrev_i32_e32 v135, 31, v134
	v_lshlrev_b64 v[134:135], 12, v[134:135]
	v_lshl_add_u64 v[134:135], s[8:9], 0, v[134:135]
	v_and_b32_e32 v131, 64, v154
	v_xor_b32_e32 v129, 16, v154
	v_add_u32_e32 v131, 64, v131
	v_cmp_lt_i32_e32 vcc, v129, v131
	s_lshl_b32 s2, s2, 3
	s_add_i32 s2, s2, 0
	v_cndmask_b32_e32 v129, v154, v129, vcc
	v_lshlrev_b32_e32 v129, 2, v129
	s_waitcnt vmcnt(8)
	v_pk_fma_f32 v[118:119], v[188:189], s[4:5], v[118:119] op_sel_hi:[1,0,1]
	v_pk_fma_f32 v[116:117], v[186:187], s[4:5], v[116:117] op_sel_hi:[1,0,1]
	v_pk_fma_f32 v[82:83], v[192:193], s[4:5], v[82:83] op_sel_hi:[1,0,1]
	v_pk_fma_f32 v[80:81], v[190:191], s[4:5], v[80:81] op_sel_hi:[1,0,1]
	v_pk_fma_f32 v[30:31], v[196:197], s[4:5], v[30:31] op_sel_hi:[1,0,1]
	v_pk_fma_f32 v[28:29], v[194:195], s[4:5], v[28:29] op_sel_hi:[1,0,1]
	v_pk_fma_f32 v[2:3], v[200:201], s[4:5], v[2:3] op_sel_hi:[1,0,1]
	v_pk_fma_f32 v[0:1], v[198:199], s[4:5], v[0:1] op_sel_hi:[1,0,1]
	v_lshl_add_u64 v[142:143], v[134:135], 0, v[132:133]
	s_mov_b32 s98, 0x30000
	v_lshl_add_u64 v[226:227], v[238:239], 0, s[98:99]
	global_load_dwordx4 v[186:189], v[226:227], off
	global_load_dwordx4 v[190:193], v[226:227], off offset:64
	global_load_dwordx4 v[194:197], v[226:227], off offset:512
	global_load_dwordx4 v[198:201], v[226:227], off offset:576
	v_or_b32_e32 v134, 48, v128
	v_ashrrev_i32_e32 v135, 31, v134
	v_lshlrev_b64 v[134:135], 12, v[134:135]
	v_lshl_add_u64 v[134:135], s[8:9], 0, v[134:135]
	v_mov_b32_e32 v172, v116
	v_mov_b32_e32 v173, v119
	v_mov_b32_e32 v174, v81
	v_mov_b32_e32 v175, v82
	v_mov_b32_e32 v176, v80
	v_mov_b32_e32 v177, v83
	v_add_f32_e32 v179, v28, v29
	v_add_f32_e32 v181, v30, v31
	v_mov_b32_e32 v178, v0
	v_mov_b32_e32 v180, v1
	v_mov_b32_e32 v182, v3
	s_waitcnt vmcnt(11)
	v_pk_fma_f32 v[126:127], v[204:205], s[4:5], v[126:127] op_sel_hi:[1,0,1]
	v_pk_fma_f32 v[124:125], v[202:203], s[4:5], v[124:125] op_sel_hi:[1,0,1]
	s_waitcnt vmcnt(10)
	v_pk_fma_f32 v[86:87], v[208:209], s[4:5], v[86:87] op_sel_hi:[1,0,1]
	v_pk_fma_f32 v[84:85], v[206:207], s[4:5], v[84:85] op_sel_hi:[1,0,1]
	s_waitcnt vmcnt(9)
	v_pk_fma_f32 v[42:43], v[212:213], s[4:5], v[42:43] op_sel_hi:[1,0,1]
	v_pk_fma_f32 v[40:41], v[210:211], s[4:5], v[40:41] op_sel_hi:[1,0,1]
	s_waitcnt vmcnt(8)
	v_pk_fma_f32 v[6:7], v[216:217], s[4:5], v[6:7] op_sel_hi:[1,0,1]
	v_pk_fma_f32 v[4:5], v[214:215], s[4:5], v[4:5] op_sel_hi:[1,0,1]
	v_lshl_add_u64 v[144:145], v[134:135], 0, v[132:133]
	s_mov_b32 s98, 0x80000
	v_lshl_add_u64 v[226:227], v[238:239], 0, s[98:99]
	global_load_dwordx4 v[202:205], v[226:227], off
	global_load_dwordx4 v[206:209], v[226:227], off offset:64
	global_load_dwordx4 v[210:213], v[226:227], off offset:512
	global_load_dwordx4 v[214:217], v[226:227], off offset:576
	v_add_u32_e32 v134, 0x80, v128
	v_ashrrev_i32_e32 v135, 31, v134
	v_lshlrev_b64 v[134:135], 12, v[134:135]
	v_lshl_add_u64 v[134:135], s[8:9], 0, v[134:135]
	s_waitcnt vmcnt(11)
	v_pk_fma_f32 v[122:123], v[220:221], s[4:5], v[122:123] op_sel_hi:[1,0,1]
	v_pk_fma_f32 v[120:121], v[218:219], s[4:5], v[120:121] op_sel_hi:[1,0,1]
	s_waitcnt vmcnt(10)
	v_pk_fma_f32 v[98:99], v[224:225], s[4:5], v[98:99] op_sel_hi:[1,0,1]
	v_pk_fma_f32 v[96:97], v[222:223], s[4:5], v[96:97] op_sel_hi:[1,0,1]
	s_waitcnt vmcnt(9)
	v_pk_fma_f32 v[46:47], v[232:233], s[4:5], v[46:47] op_sel_hi:[1,0,1]
	v_pk_fma_f32 v[44:45], v[230:231], s[4:5], v[44:45] op_sel_hi:[1,0,1]
	s_waitcnt vmcnt(8)
	v_pk_fma_f32 v[10:11], v[236:237], s[4:5], v[10:11] op_sel_hi:[1,0,1]
	v_pk_fma_f32 v[8:9], v[234:235], s[4:5], v[8:9] op_sel_hi:[1,0,1]
	v_lshl_add_u64 v[146:147], v[134:135], 0, v[132:133]
	s_mov_b32 s98, 0x90000
	v_lshl_add_u64 v[226:227], v[238:239], 0, s[98:99]
	global_load_dwordx4 v[218:221], v[226:227], off
	global_load_dwordx4 v[222:225], v[226:227], off offset:64
	global_load_dwordx4 v[230:233], v[226:227], off offset:512
	global_load_dwordx4 v[234:237], v[226:227], off offset:576
	v_add_u32_e32 v134, 0x90, v128
	v_ashrrev_i32_e32 v135, 31, v134
	v_lshlrev_b64 v[134:135], 12, v[134:135]
	v_lshl_add_u64 v[134:135], s[8:9], 0, v[134:135]
	s_waitcnt vmcnt(11)
	v_pk_fma_f32 v[114:115], v[188:189], s[4:5], v[114:115] op_sel_hi:[1,0,1]
	v_pk_fma_f32 v[112:113], v[186:187], s[4:5], v[112:113] op_sel_hi:[1,0,1]
	s_waitcnt vmcnt(10)
	v_pk_fma_f32 v[102:103], v[192:193], s[4:5], v[102:103] op_sel_hi:[1,0,1]
	v_pk_fma_f32 v[100:101], v[190:191], s[4:5], v[100:101] op_sel_hi:[1,0,1]
	s_waitcnt vmcnt(9)
	v_pk_fma_f32 v[58:59], v[196:197], s[4:5], v[58:59] op_sel_hi:[1,0,1]
	v_pk_fma_f32 v[56:57], v[194:195], s[4:5], v[56:57] op_sel_hi:[1,0,1]
	s_waitcnt vmcnt(8)
	v_pk_fma_f32 v[14:15], v[200:201], s[4:5], v[14:15] op_sel_hi:[1,0,1]
	v_pk_fma_f32 v[12:13], v[198:199], s[4:5], v[12:13] op_sel_hi:[1,0,1]
	v_lshl_add_u64 v[148:149], v[134:135], 0, v[132:133]
	s_mov_b32 s98, 0xa0000
	v_lshl_add_u64 v[226:227], v[238:239], 0, s[98:99]
	global_load_dwordx4 v[186:189], v[226:227], off
	global_load_dwordx4 v[190:193], v[226:227], off offset:64
	global_load_dwordx4 v[194:197], v[226:227], off offset:512
	global_load_dwordx4 v[198:201], v[226:227], off offset:576
	v_add_u32_e32 v134, 0xa0, v128
	v_ashrrev_i32_e32 v135, 31, v134
	v_lshlrev_b64 v[134:135], 12, v[134:135]
	v_lshl_add_u64 v[134:135], s[8:9], 0, v[134:135]
	s_waitcnt vmcnt(11)
	v_pk_fma_f32 v[110:111], v[204:205], s[4:5], v[110:111] op_sel_hi:[1,0,1]
	v_pk_fma_f32 v[108:109], v[202:203], s[4:5], v[108:109] op_sel_hi:[1,0,1]
	s_waitcnt vmcnt(10)
	v_pk_fma_f32 v[106:107], v[208:209], s[4:5], v[106:107] op_sel_hi:[1,0,1]
	v_pk_fma_f32 v[104:105], v[206:207], s[4:5], v[104:105] op_sel_hi:[1,0,1]
	s_waitcnt vmcnt(9)
	v_pk_fma_f32 v[62:63], v[212:213], s[4:5], v[62:63] op_sel_hi:[1,0,1]
	v_pk_fma_f32 v[60:61], v[210:211], s[4:5], v[60:61] op_sel_hi:[1,0,1]
	s_waitcnt vmcnt(8)
	v_pk_fma_f32 v[18:19], v[216:217], s[4:5], v[18:19] op_sel_hi:[1,0,1]
	v_pk_fma_f32 v[16:17], v[214:215], s[4:5], v[16:17] op_sel_hi:[1,0,1]
	v_lshl_add_u64 v[150:151], v[134:135], 0, v[132:133]
	s_mov_b32 s98, 0xb0000
	v_lshl_add_u64 v[226:227], v[238:239], 0, s[98:99]
	global_load_dwordx4 v[202:205], v[226:227], off
	global_load_dwordx4 v[206:209], v[226:227], off offset:64
	global_load_dwordx4 v[210:213], v[226:227], off offset:512
	global_load_dwordx4 v[214:217], v[226:227], off offset:576
	v_add_u32_e32 v134, 0xb0, v128
	v_ashrrev_i32_e32 v135, 31, v134
	v_lshlrev_b64 v[134:135], 12, v[134:135]
	v_lshl_add_u64 v[134:135], s[8:9], 0, v[134:135]
	v_lshl_add_u64 v[152:153], v[134:135], 0, v[132:133]
	v_mov_b32_e32 v134, v117
	v_mov_b32_e32 v135, v118
	v_pk_add_f32 v[134:135], v[134:135], v[172:173]
	v_pk_add_f32 v[172:173], v[174:175], v[176:177]
	v_add_f32_e32 v128, v134, v135
	v_pk_add_f32 v[134:135], v[172:173], v[172:173] op_sel_hi:[0,1]
	v_add_f32_e32 v183, 0, v128
	v_mov_b32_e32 v134, v2
	v_pk_add_f32 v[174:175], v[178:179], v[180:181]
	v_pk_add_f32 v[134:135], v[134:135], v[182:183]
	v_xor_b32_e32 v128, 32, v154
	v_pk_add_f32 v[134:135], v[174:175], v[134:135]
	v_cmp_lt_i32_e32 vcc, v128, v131
	v_add_f32_e32 v134, v134, v135
	ds_bpermute_b32 v135, v129, v134
	v_cndmask_b32_e32 v128, v154, v128, vcc
	v_lshlrev_b32_e32 v128, 2, v128
	v_cmp_gt_u32_e32 vcc, 16, v130
	s_waitcnt lgkmcnt(0)
	v_add_f32_e32 v131, v134, v135
	ds_bpermute_b32 v134, v128, v131
	s_waitcnt lgkmcnt(0)
	v_add_f32_e32 v131, v131, v134
	v_fmamk_f32 v135, v131, 0xbc800000, v119
	v_fmamk_f32 v172, v131, 0xbc800000, v117
	v_fmamk_f32 v174, v131, 0xbc800000, v83
	v_fmamk_f32 v176, v131, 0xbc800000, v81
	v_fmamk_f32 v134, v131, 0xbc800000, v118
	v_fmamk_f32 v154, v131, 0xbc800000, v116
	v_fmamk_f32 v173, v131, 0xbc800000, v82
	v_fmamk_f32 v175, v131, 0xbc800000, v80
	v_fmamk_f32 v178, v131, 0xbc800000, v31
	v_fmamk_f32 v180, v131, 0xbc800000, v29
	v_mul_f32_e32 v172, v172, v172
	v_mul_f32_e32 v135, v135, v135
	v_mul_f32_e32 v176, v176, v176
	v_mul_f32_e32 v174, v174, v174
	v_fmamk_f32 v177, v131, 0xbc800000, v30
	v_fmamk_f32 v179, v131, 0xbc800000, v28
	v_fmamk_f32 v182, v131, 0xbc800000, v3
	v_fmamk_f32 v184, v131, 0xbc800000, v1
	v_mul_f32_e32 v180, v180, v180
	v_mul_f32_e32 v178, v178, v178
	v_fmac_f32_e32 v172, v154, v154
	v_fmac_f32_e32 v135, v134, v134
	v_fmac_f32_e32 v176, v175, v175
	v_fmac_f32_e32 v174, v173, v173
	v_fmamk_f32 v181, v131, 0xbc800000, v2
	v_fmamk_f32 v183, v131, 0xbc800000, v0
	v_mul_f32_e32 v184, v184, v184
	v_mul_f32_e32 v182, v182, v182
	v_fmac_f32_e32 v180, v179, v179
	v_fmac_f32_e32 v178, v177, v177
	v_add_f32_e32 v134, v172, v135
	v_add_f32_e32 v135, v176, v174
	v_fmac_f32_e32 v184, v183, v183
	v_fmac_f32_e32 v182, v181, v181
	v_add_f32_e32 v154, v180, v178
	v_add_f32_e32 v134, v134, v135
	v_add_f32_e32 v172, v184, v182
	v_add_f32_e32 v134, v154, v134
	v_add_f32_e32 v134, v172, v134
	ds_bpermute_b32 v135, v129, v134
	s_waitcnt lgkmcnt(0)
	v_add_f32_e32 v134, v134, v135
	s_waitcnt vmcnt(11)
	v_pk_fma_f32 v[94:95], v[220:221], s[4:5], v[94:95] op_sel_hi:[1,0,1]
	v_pk_fma_f32 v[92:93], v[218:219], s[4:5], v[92:93] op_sel_hi:[1,0,1]
	s_waitcnt vmcnt(10)
	v_pk_fma_f32 v[90:91], v[224:225], s[4:5], v[90:91] op_sel_hi:[1,0,1]
	v_pk_fma_f32 v[88:89], v[222:223], s[4:5], v[88:89] op_sel_hi:[1,0,1]
	s_waitcnt vmcnt(9)
	v_pk_fma_f32 v[70:71], v[232:233], s[4:5], v[70:71] op_sel_hi:[1,0,1]
	v_pk_fma_f32 v[68:69], v[230:231], s[4:5], v[68:69] op_sel_hi:[1,0,1]
	s_waitcnt vmcnt(8)
	v_pk_fma_f32 v[22:23], v[236:237], s[4:5], v[22:23] op_sel_hi:[1,0,1]
	v_pk_fma_f32 v[20:21], v[234:235], s[4:5], v[20:21] op_sel_hi:[1,0,1]
	ds_bpermute_b32 v135, v128, v134
	s_waitcnt vmcnt(7)
	v_pk_fma_f32 v[78:79], v[188:189], s[4:5], v[78:79] op_sel_hi:[1,0,1]
	v_pk_fma_f32 v[76:77], v[186:187], s[4:5], v[76:77] op_sel_hi:[1,0,1]
	s_waitcnt vmcnt(6)
	v_pk_fma_f32 v[74:75], v[192:193], s[4:5], v[74:75] op_sel_hi:[1,0,1]
	v_pk_fma_f32 v[72:73], v[190:191], s[4:5], v[72:73] op_sel_hi:[1,0,1]
	s_waitcnt vmcnt(5)
	v_pk_fma_f32 v[66:67], v[196:197], s[4:5], v[66:67] op_sel_hi:[1,0,1]
	v_pk_fma_f32 v[64:65], v[194:195], s[4:5], v[64:65] op_sel_hi:[1,0,1]
	s_waitcnt vmcnt(4)
	v_pk_fma_f32 v[26:27], v[200:201], s[4:5], v[26:27] op_sel_hi:[1,0,1]
	v_pk_fma_f32 v[24:25], v[198:199], s[4:5], v[24:25] op_sel_hi:[1,0,1]
	s_nop 0
	s_waitcnt vmcnt(3)
	v_pk_fma_f32 v[54:55], v[204:205], s[4:5], v[54:55] op_sel_hi:[1,0,1]
	v_pk_fma_f32 v[52:53], v[202:203], s[4:5], v[52:53] op_sel_hi:[1,0,1]
	s_waitcnt vmcnt(2)
	v_pk_fma_f32 v[50:51], v[208:209], s[4:5], v[50:51] op_sel_hi:[1,0,1]
	v_pk_fma_f32 v[48:49], v[206:207], s[4:5], v[48:49] op_sel_hi:[1,0,1]
	s_waitcnt vmcnt(1)
	v_pk_fma_f32 v[38:39], v[212:213], s[4:5], v[38:39] op_sel_hi:[1,0,1]
	v_pk_fma_f32 v[36:37], v[210:211], s[4:5], v[36:37] op_sel_hi:[1,0,1]
	s_waitcnt vmcnt(0)
	v_pk_fma_f32 v[34:35], v[216:217], s[4:5], v[34:35] op_sel_hi:[1,0,1]
	v_pk_fma_f32 v[32:33], v[214:215], s[4:5], v[32:33] op_sel_hi:[1,0,1]
	s_nop 0
	s_and_saveexec_b64 s[4:5], vcc
	v_readlane_b32 s28, v244, 7
	v_readlane_b32 s24, v244, 9
	v_readlane_b32 s29, v244, 8
	v_readlane_b32 s25, v244, 10
	s_cbranch_execz .LBB0_1563
	s_lshl_b32 s6, s1, 11
	s_add_i32 s6, s2, s6
	v_mul_f32_e32 v156, 0x3c800000, v131
	v_lshl_add_u32 v131, v130, 5, s6
	s_waitcnt lgkmcnt(0)
	v_add_f32_e32 v157, v134, v135
	ds_write_b64 v131, v[156:157]

.LBB0_1818:
	v_mov_b32_e32 v130, v144
	s_lshl_b32 s0, s3, 5
	s_barrier
	s_lshl_b32 s1, s18, 8
	v_ashrrev_i32_e32 v128, 2, v130
	s_or_b32 s0, s1, s0
	v_and_b32_e32 v128, -4, v128
	s_lshl_b32 s22, s21, 8
	v_and_b32_e32 v138, 15, v130
	v_add_u32_e32 v132, s0, v128
	s_add_i32 s0, s22, s20
	v_or_b32_e32 v128, s0, v138
	v_ashrrev_i32_e32 v129, 31, v128
	v_ashrrev_i32_e32 v133, 31, v132
	v_lshlrev_b64 v[134:135], 12, v[128:129]
	v_lshl_add_u64 v[134:135], s[12:13], 0, v[134:135]
	v_lshlrev_b64 v[136:137], 2, v[132:133]
	v_lshl_add_u64 v[150:151], v[134:135], 0, v[136:137]
	v_mov_b32_e32 v236, v150
	v_mov_b32_e32 v237, v151
	s_mov_b32 s99, 0
	global_load_dwordx4 v[168:171], v[150:151], off
	global_load_dwordx4 v[172:175], v[150:151], off offset:64
	global_load_dwordx4 v[176:179], v[150:151], off offset:512
	global_load_dwordx4 v[180:183], v[150:151], off offset:576
	s_mov_b32 s98, 0x10000
	v_lshl_add_u64 v[234:235], v[236:237], 0, s[98:99]
	global_load_dwordx4 v[184:187], v[234:235], off
	global_load_dwordx4 v[188:191], v[234:235], off offset:64
	global_load_dwordx4 v[192:195], v[234:235], off offset:512
	global_load_dwordx4 v[196:199], v[234:235], off offset:576
	s_mov_b32 s98, 0x20000
	v_lshl_add_u64 v[234:235], v[236:237], 0, s[98:99]
	global_load_dwordx4 v[200:203], v[234:235], off
	global_load_dwordx4 v[204:207], v[234:235], off offset:64
	global_load_dwordx4 v[208:211], v[234:235], off offset:512
	global_load_dwordx4 v[212:215], v[234:235], off offset:576
	s_mov_b32 s98, 0x30000
	v_lshl_add_u64 v[234:235], v[236:237], 0, s[98:99]
	global_load_dwordx4 v[216:219], v[234:235], off
	global_load_dwordx4 v[220:223], v[234:235], off offset:64
	global_load_dwordx4 v[224:227], v[234:235], off offset:512
	global_load_dwordx4 v[230:233], v[234:235], off offset:576
	v_or_b32_e32 v154, 16, v128
	v_ashrrev_i32_e32 v155, 31, v154
	v_lshlrev_b64 v[154:155], 12, v[154:155]
	s_mov_b32 s0, 0x3fb504f3
	v_lshl_add_u64 v[154:155], s[12:13], 0, v[154:155]
	v_lshl_add_u64 v[154:155], v[154:155], 0, v[136:137]
	v_and_b32_e32 v131, 64, v144
	v_xor_b32_e32 v129, 16, v144
	v_add_u32_e32 v131, 64, v131
	v_cmp_lt_i32_e32 vcc, v129, v131
	s_waitcnt vmcnt(12)
	v_pk_fma_f32 v[114:115], v[170:171], s[0:1], v[114:115] op_sel_hi:[1,0,1]
	v_pk_fma_f32 v[112:113], v[168:169], s[0:1], v[112:113] op_sel_hi:[1,0,1]
	v_pk_fma_f32 v[90:91], v[174:175], s[0:1], v[90:91] op_sel_hi:[1,0,1]
	v_pk_fma_f32 v[88:89], v[172:173], s[0:1], v[88:89] op_sel_hi:[1,0,1]
	v_pk_fma_f32 v[54:55], v[178:179], s[0:1], v[54:55] op_sel_hi:[1,0,1]
	v_pk_fma_f32 v[52:53], v[176:177], s[0:1], v[52:53] op_sel_hi:[1,0,1]
	v_pk_fma_f32 v[10:11], v[182:183], s[0:1], v[10:11] op_sel_hi:[1,0,1]
	v_pk_fma_f32 v[8:9], v[180:181], s[0:1], v[8:9] op_sel_hi:[1,0,1]
	v_cndmask_b32_e32 v129, v144, v129, vcc
	s_mov_b32 s98, 0x80000
	v_lshl_add_u64 v[234:235], v[236:237], 0, s[98:99]
	global_load_dwordx4 v[168:171], v[234:235], off
	global_load_dwordx4 v[172:175], v[234:235], off offset:64
	global_load_dwordx4 v[176:179], v[234:235], off offset:512
	global_load_dwordx4 v[180:183], v[234:235], off offset:576
	v_or_b32_e32 v154, 32, v128
	v_ashrrev_i32_e32 v155, 31, v154
	v_lshlrev_b64 v[154:155], 12, v[154:155]
	v_lshl_add_u64 v[154:155], s[12:13], 0, v[154:155]
	v_lshl_add_u64 v[154:155], v[154:155], 0, v[136:137]
	v_mov_b32_e32 v158, v113
	v_mov_b32_e32 v159, v114
	v_mov_b32_e32 v160, v112
	v_mov_b32_e32 v161, v115
	v_mov_b32_e32 v162, v89
	v_mov_b32_e32 v163, v90
	v_pk_add_f32 v[158:159], v[158:159], v[160:161]
	v_add_f32_e32 v165, v54, v55
	v_mov_b32_e32 v164, v9
	v_mov_b32_e32 v166, v11
	v_lshlrev_b32_e32 v129, 2, v129
	s_waitcnt vmcnt(15)
	v_pk_fma_f32 v[122:123], v[186:187], s[0:1], v[122:123] op_sel_hi:[1,0,1]
	v_pk_fma_f32 v[120:121], v[184:185], s[0:1], v[120:121] op_sel_hi:[1,0,1]
	s_waitcnt vmcnt(14)
	v_pk_fma_f32 v[102:103], v[190:191], s[0:1], v[102:103] op_sel_hi:[1,0,1]
	v_pk_fma_f32 v[100:101], v[188:189], s[0:1], v[100:101] op_sel_hi:[1,0,1]
	s_waitcnt vmcnt(13)
	v_pk_fma_f32 v[62:63], v[194:195], s[0:1], v[62:63] op_sel_hi:[1,0,1]
	v_pk_fma_f32 v[60:61], v[192:193], s[0:1], v[60:61] op_sel_hi:[1,0,1]
	s_waitcnt vmcnt(12)
	v_pk_fma_f32 v[22:23], v[198:199], s[0:1], v[22:23] op_sel_hi:[1,0,1]
	v_pk_fma_f32 v[20:21], v[196:197], s[0:1], v[20:21] op_sel_hi:[1,0,1]
	s_nop 0
	s_mov_b32 s98, 0x90000
	v_lshl_add_u64 v[234:235], v[236:237], 0, s[98:99]
	global_load_dwordx4 v[184:187], v[234:235], off
	global_load_dwordx4 v[188:191], v[234:235], off offset:64
	global_load_dwordx4 v[192:195], v[234:235], off offset:512
	global_load_dwordx4 v[196:199], v[234:235], off offset:576
	v_or_b32_e32 v154, 48, v128
	v_ashrrev_i32_e32 v155, 31, v154
	v_lshlrev_b64 v[154:155], 12, v[154:155]
	v_lshl_add_u64 v[154:155], s[12:13], 0, v[154:155]
	v_lshl_add_u64 v[154:155], v[154:155], 0, v[136:137]
	s_waitcnt vmcnt(15)
	v_pk_fma_f32 v[126:127], v[202:203], s[0:1], v[126:127] op_sel_hi:[1,0,1]
	v_pk_fma_f32 v[124:125], v[200:201], s[0:1], v[124:125] op_sel_hi:[1,0,1]
	s_waitcnt vmcnt(14)
	v_pk_fma_f32 v[106:107], v[206:207], s[0:1], v[106:107] op_sel_hi:[1,0,1]
	v_pk_fma_f32 v[104:105], v[204:205], s[0:1], v[104:105] op_sel_hi:[1,0,1]
	s_waitcnt vmcnt(13)
	v_pk_fma_f32 v[70:71], v[210:211], s[0:1], v[70:71] op_sel_hi:[1,0,1]
	v_pk_fma_f32 v[68:69], v[208:209], s[0:1], v[68:69] op_sel_hi:[1,0,1]
	s_waitcnt vmcnt(12)
	v_pk_fma_f32 v[30:31], v[214:215], s[0:1], v[30:31] op_sel_hi:[1,0,1]
	v_pk_fma_f32 v[28:29], v[212:213], s[0:1], v[28:29] op_sel_hi:[1,0,1]
	s_nop 0
	s_mov_b32 s98, 0xa0000
	v_lshl_add_u64 v[234:235], v[236:237], 0, s[98:99]
	global_load_dwordx4 v[200:203], v[234:235], off
	global_load_dwordx4 v[204:207], v[234:235], off offset:64
	global_load_dwordx4 v[208:211], v[234:235], off offset:512
	global_load_dwordx4 v[212:215], v[234:235], off offset:576
	v_add_u32_e32 v154, 0x80, v128
	v_ashrrev_i32_e32 v155, 31, v154
	v_lshlrev_b64 v[154:155], 12, v[154:155]
	v_lshl_add_u64 v[154:155], s[12:13], 0, v[154:155]
	v_lshl_add_u64 v[154:155], v[154:155], 0, v[136:137]
	s_waitcnt vmcnt(15)
	v_pk_fma_f32 v[118:119], v[218:219], s[0:1], v[118:119] op_sel_hi:[1,0,1]
	v_pk_fma_f32 v[116:117], v[216:217], s[0:1], v[116:117] op_sel_hi:[1,0,1]
	s_waitcnt vmcnt(14)
	v_pk_fma_f32 v[110:111], v[222:223], s[0:1], v[110:111] op_sel_hi:[1,0,1]
	v_pk_fma_f32 v[108:109], v[220:221], s[0:1], v[108:109] op_sel_hi:[1,0,1]
	s_waitcnt vmcnt(13)
	v_pk_fma_f32 v[78:79], v[226:227], s[0:1], v[78:79] op_sel_hi:[1,0,1]
	v_pk_fma_f32 v[76:77], v[224:225], s[0:1], v[76:77] op_sel_hi:[1,0,1]
	s_waitcnt vmcnt(12)
	v_pk_fma_f32 v[38:39], v[232:233], s[0:1], v[38:39] op_sel_hi:[1,0,1]
	v_pk_fma_f32 v[36:37], v[230:231], s[0:1], v[36:37] op_sel_hi:[1,0,1]
	s_nop 0
	s_mov_b32 s98, 0xb0000
	v_lshl_add_u64 v[234:235], v[236:237], 0, s[98:99]
	global_load_dwordx4 v[216:219], v[234:235], off
	global_load_dwordx4 v[220:223], v[234:235], off offset:64
	global_load_dwordx4 v[224:227], v[234:235], off offset:512
	global_load_dwordx4 v[230:233], v[234:235], off offset:576
	v_add_u32_e32 v154, 0x90, v128
	v_ashrrev_i32_e32 v155, 31, v154
	v_lshlrev_b64 v[154:155], 12, v[154:155]
	v_lshl_add_u64 v[154:155], s[12:13], 0, v[154:155]
	v_lshl_add_u64 v[154:155], v[154:155], 0, v[136:137]
	s_waitcnt vmcnt(15)
	v_pk_fma_f32 v[98:99], v[170:171], s[0:1], v[98:99] op_sel_hi:[1,0,1]
	v_pk_fma_f32 v[96:97], v[168:169], s[0:1], v[96:97] op_sel_hi:[1,0,1]
	s_waitcnt vmcnt(14)
	v_pk_fma_f32 v[94:95], v[174:175], s[0:1], v[94:95] op_sel_hi:[1,0,1]
	v_pk_fma_f32 v[92:93], v[172:173], s[0:1], v[92:93] op_sel_hi:[1,0,1]
	s_waitcnt vmcnt(13)
	v_pk_fma_f32 v[86:87], v[178:179], s[0:1], v[86:87] op_sel_hi:[1,0,1]
	v_pk_fma_f32 v[84:85], v[176:177], s[0:1], v[84:85] op_sel_hi:[1,0,1]
	s_waitcnt vmcnt(12)
	v_pk_fma_f32 v[50:51], v[182:183], s[0:1], v[50:51] op_sel_hi:[1,0,1]
	v_pk_fma_f32 v[48:49], v[180:181], s[0:1], v[48:49] op_sel_hi:[1,0,1]
	s_nop 0
	v_add_u32_e32 v154, 0xa0, v128
	v_ashrrev_i32_e32 v155, 31, v154
	v_lshlrev_b64 v[154:155], 12, v[154:155]
	v_lshl_add_u64 v[154:155], s[12:13], 0, v[154:155]
	v_lshl_add_u64 v[154:155], v[154:155], 0, v[136:137]
	s_waitcnt vmcnt(11)
	v_pk_fma_f32 v[82:83], v[186:187], s[0:1], v[82:83] op_sel_hi:[1,0,1]
	v_pk_fma_f32 v[80:81], v[184:185], s[0:1], v[80:81] op_sel_hi:[1,0,1]
	s_waitcnt vmcnt(10)
	v_pk_fma_f32 v[74:75], v[190:191], s[0:1], v[74:75] op_sel_hi:[1,0,1]
	v_pk_fma_f32 v[72:73], v[188:189], s[0:1], v[72:73] op_sel_hi:[1,0,1]
	s_waitcnt vmcnt(9)
	v_pk_fma_f32 v[66:67], v[194:195], s[0:1], v[66:67] op_sel_hi:[1,0,1]
	v_pk_fma_f32 v[64:65], v[192:193], s[0:1], v[64:65] op_sel_hi:[1,0,1]
	s_waitcnt vmcnt(8)
	v_pk_fma_f32 v[58:59], v[198:199], s[0:1], v[58:59] op_sel_hi:[1,0,1]
	v_pk_fma_f32 v[56:57], v[196:197], s[0:1], v[56:57] op_sel_hi:[1,0,1]
	s_nop 0
	v_add_u32_e32 v154, 0xb0, v128
	v_ashrrev_i32_e32 v155, 31, v154
	v_lshlrev_b64 v[154:155], 12, v[154:155]
	v_lshl_add_u64 v[154:155], s[12:13], 0, v[154:155]
	v_lshl_add_u64 v[154:155], v[154:155], 0, v[136:137]
	v_add_f32_e32 v128, v158, v159
	v_add_f32_e32 v167, 0, v128
	v_xor_b32_e32 v128, 32, v144
	v_cmp_lt_i32_e32 vcc, v128, v131
	s_waitcnt vmcnt(7)
	v_pk_fma_f32 v[46:47], v[202:203], s[0:1], v[46:47] op_sel_hi:[1,0,1]
	v_pk_fma_f32 v[44:45], v[200:201], s[0:1], v[44:45] op_sel_hi:[1,0,1]
	s_waitcnt vmcnt(6)
	v_pk_fma_f32 v[42:43], v[206:207], s[0:1], v[42:43] op_sel_hi:[1,0,1]
	v_pk_fma_f32 v[40:41], v[204:205], s[0:1], v[40:41] op_sel_hi:[1,0,1]
	s_waitcnt vmcnt(5)
	v_pk_fma_f32 v[34:35], v[210:211], s[0:1], v[34:35] op_sel_hi:[1,0,1]
	v_pk_fma_f32 v[32:33], v[208:209], s[0:1], v[32:33] op_sel_hi:[1,0,1]
	s_waitcnt vmcnt(4)
	v_pk_fma_f32 v[26:27], v[214:215], s[0:1], v[26:27] op_sel_hi:[1,0,1]
	v_pk_fma_f32 v[24:25], v[212:213], s[0:1], v[24:25] op_sel_hi:[1,0,1]
	v_mov_b32_e32 v132, v88
	v_mov_b32_e32 v133, v91
	v_pk_add_f32 v[132:133], v[162:163], v[132:133]
	v_add_f32_e32 v135, v52, v53
	v_pk_add_f32 v[132:133], v[132:133], v[132:133] op_sel_hi:[0,1]
	v_mov_b32_e32 v134, v8
	v_mov_b32_e32 v132, v10
	v_pk_add_f32 v[134:135], v[134:135], v[164:165]
	v_pk_add_f32 v[132:133], v[132:133], v[166:167]
	v_cndmask_b32_e32 v128, v144, v128, vcc
	v_pk_add_f32 v[132:133], v[134:135], v[132:133]
	v_lshlrev_b32_e32 v128, 2, v128
	v_add_f32_e32 v132, v132, v133
	ds_bpermute_b32 v133, v129, v132
	v_cmp_gt_u32_e32 vcc, 16, v130
	s_waitcnt lgkmcnt(0)
	v_add_f32_e32 v131, v132, v133
	ds_bpermute_b32 v132, v128, v131
	s_waitcnt lgkmcnt(0)
	v_add_f32_e32 v131, v131, v132
	v_fmamk_f32 v133, v131, 0xbc800000, v115
	v_fmamk_f32 v135, v131, 0xbc800000, v113
	v_fmamk_f32 v144, v131, 0xbc800000, v91
	v_fmamk_f32 v158, v131, 0xbc800000, v89
	v_fmamk_f32 v132, v131, 0xbc800000, v114
	v_fmamk_f32 v134, v131, 0xbc800000, v112
	v_fmamk_f32 v139, v131, 0xbc800000, v90
	v_fmamk_f32 v145, v131, 0xbc800000, v88
	v_fmamk_f32 v160, v131, 0xbc800000, v55
	v_fmamk_f32 v162, v131, 0xbc800000, v53
	v_mul_f32_e32 v135, v135, v135
	v_mul_f32_e32 v133, v133, v133
	v_mul_f32_e32 v158, v158, v158
	v_mul_f32_e32 v144, v144, v144
	v_fmamk_f32 v159, v131, 0xbc800000, v54
	v_fmamk_f32 v161, v131, 0xbc800000, v52
	v_fmamk_f32 v164, v131, 0xbc800000, v11
	v_fmamk_f32 v166, v131, 0xbc800000, v9
	v_mul_f32_e32 v162, v162, v162
	v_mul_f32_e32 v160, v160, v160
	v_fmac_f32_e32 v135, v134, v134
	v_fmac_f32_e32 v133, v132, v132
	v_fmac_f32_e32 v158, v145, v145
	v_fmac_f32_e32 v144, v139, v139
	v_fmamk_f32 v163, v131, 0xbc800000, v10
	v_fmamk_f32 v165, v131, 0xbc800000, v8
	v_mul_f32_e32 v166, v166, v166
	v_mul_f32_e32 v164, v164, v164
	v_fmac_f32_e32 v162, v161, v161
	v_fmac_f32_e32 v160, v159, v159
	v_add_f32_e32 v132, v135, v133
	v_add_f32_e32 v133, v158, v144
	v_fmac_f32_e32 v166, v165, v165
	v_fmac_f32_e32 v164, v163, v163
	v_add_f32_e32 v134, v162, v160
	v_add_f32_e32 v132, v132, v133
	v_add_f32_e32 v135, v166, v164
	v_add_f32_e32 v132, v134, v132
	v_add_f32_e32 v132, v135, v132
	ds_bpermute_b32 v133, v129, v132
	s_waitcnt lgkmcnt(0)
	v_add_f32_e32 v132, v132, v133
	ds_bpermute_b32 v133, v128, v132
	s_waitcnt vmcnt(3)
	v_pk_fma_f32 v[18:19], v[218:219], s[0:1], v[18:19] op_sel_hi:[1,0,1]
	v_pk_fma_f32 v[16:17], v[216:217], s[0:1], v[16:17] op_sel_hi:[1,0,1]
	s_waitcnt vmcnt(2)
	v_pk_fma_f32 v[14:15], v[222:223], s[0:1], v[14:15] op_sel_hi:[1,0,1]
	v_pk_fma_f32 v[12:13], v[220:221], s[0:1], v[12:13] op_sel_hi:[1,0,1]
	s_waitcnt vmcnt(1)
	v_pk_fma_f32 v[6:7], v[226:227], s[0:1], v[6:7] op_sel_hi:[1,0,1]
	v_pk_fma_f32 v[4:5], v[224:225], s[0:1], v[4:5] op_sel_hi:[1,0,1]
	s_waitcnt vmcnt(0)
	v_pk_fma_f32 v[2:3], v[232:233], s[0:1], v[2:3] op_sel_hi:[1,0,1]
	v_pk_fma_f32 v[0:1], v[230:231], s[0:1], v[0:1] op_sel_hi:[1,0,1]
	s_lshl_b32 s0, s3, 3
	s_add_i32 s3, s0, 0
	s_and_saveexec_b64 s[0:1], vcc
	v_readlane_b32 s28, v244, 7
	v_readlane_b32 s29, v244, 8
	s_cbranch_execz .LBB0_1820
	s_lshl_b32 s4, s2, 11
	s_add_i32 s4, s3, s4
	v_mul_f32_e32 v134, 0x3c800000, v131
	v_lshl_add_u32 v131, v130, 5, s4
	s_waitcnt lgkmcnt(0)
	v_add_f32_e32 v135, v132, v133
	ds_write_b64 v131, v[134:135]
